# RWKV prompt loop: output stage of chunk c deferred behind the next chunk's LoRA barrier (two barriers per chunk; decay and bonus tiles double-buffered), code placement +12 bytes
# speedup vs baseline: 1.0122x; 1.0002x over previous
.LBB0_1228:
	s_or_b64 exec, exec, s[14:15]
	v_and_b32_e32 v59, 63, v56
	v_lshrrev_b32_e32 v60, 3, v59
	v_ashrrev_i32_e32 v59, 5, v56
	v_and_b32_e32 v93, 7, v56
	v_lshl_add_u32 v56, v63, 2, 0
	v_lshlrev_b32_e32 v63, 1, v63
	v_lshl_add_u32 v61, v67, 2, v56
	v_sub_u32_e32 v56, v56, v63
	v_lshlrev_b32_e32 v63, 1, v67
	v_lshlrev_b32_e32 v71, 8, v62
	v_lshlrev_b32_e32 v62, 7, v62
	v_lshlrev_b32_e32 v67, 2, v66
	v_add3_u32 v109, v56, v63, v62
	s_movk_i32 s24, 0x710
	v_lshl_or_b32 v63, v59, 6, v66
	v_add_u32_e32 v68, 0, v67
	v_mul_lo_u32 v56, v59, s24
	v_lshlrev_b32_e32 v66, 2, v63
	v_lshl_or_b32 v108, v57, 3, v60
	v_mov_b32_e32 v77, 0
	v_lshlrev_b32_e32 v69, 2, v65
	v_add_u32_e32 v62, 0, v56
	v_add_u32_e32 v92, 0, v66
	v_add_u32_e32 v111, v68, v56
	v_and_b32_e32 v56, 32, v174
	s_add_i32 s16, 0, 0x16200
	s_movk_i32 s17, 0xf8f4
	v_lshl_add_u64 v[90:91], s[12:13], 0, v[76:77]
	v_sub_u32_e32 v69, v68, v69
	v_cmp_eq_u32_e64 s[12:13], 0, v56
	v_add_u32_e32 v112, s16, v66
	v_mul_lo_u32 v56, v59, s17
	v_lshl_add_u32 v115, v108, 2, s16
	v_mad_u64_u32 v[94:95], s[16:17], v63, 28, v[92:93]
	v_lshl_add_u32 v113, v59, 7, v69
	v_cmp_gt_i32_e64 s[16:17], 16, v59
	v_add_u32_e32 v95, s3, v59
	v_mul_lo_u32 v59, v89, s24
	v_add_u32_e32 v66, 0, v59
	v_mov_b32_e32 v59, 0x1540
	v_mov_b32_e32 v68, s29
	v_cmp_gt_u32_e32 vcc, 24, v58
	v_add_u32_e32 v110, v62, v67
	v_lshlrev_b32_e32 v67, 5, v58
	v_cndmask_b32_e32 v59, v59, v68, vcc
	v_mov_b32_e32 v68, s28
	v_cmp_gt_u32_e32 vcc, 16, v58
	v_lshlrev_b32_e32 v70, 2, v93
	s_movk_i32 s25, 0xffe4
	v_cndmask_b32_e32 v59, v59, v68, vcc
	v_mov_b32_e32 v68, s5
	v_cmp_gt_i32_e32 vcc, 8, v58
	v_cmp_eq_u32_e64 s[14:15], 0, v65
	v_mul_u32_u24_e32 v65, 12, v93
	v_cndmask_b32_e32 v59, v59, v68, vcc
	v_lshl_add_u32 v58, v58, 3, v59
	v_ashrrev_i32_e32 v59, 31, v58
	v_lshl_add_u64 v[96:97], v[58:59], 1, s[22:23]
	v_mov_b32_e32 v58, 0x140
	v_cndmask_b32_e64 v76, v58, 64, s[18:19]
	v_mov_b32_e32 v58, 0x180
	v_mov_b32_e32 v59, 0x80
	v_cndmask_b32_e64 v98, v58, v59, s[18:19]
	v_mov_b32_e32 v58, 0x1c0
	v_mov_b32_e32 v59, 0xc0
	v_cndmask_b32_e64 v100, v58, v59, s[18:19]
	v_mov_b32_e32 v58, 0x100
	v_cndmask_b32_e64 v102, v58, 0, s[18:19]
	v_lshlrev_b32_e32 v58, 1, v64
	v_mov_b32_e32 v59, v77
	v_lshl_add_u64 v[106:107], s[20:21], 0, v[58:59]
	v_lshlrev_b32_e32 v58, 8, v57
	v_lshlrev_b32_e32 v59, 5, v60
	v_or3_b32 v58, v58, v59, v70
	v_mul_lo_u32 v63, v63, s25
	v_add_u32_e32 v116, 0xe200, v58
	s_movk_i32 s5, 0x7180
	v_lshlrev_b32_e32 v58, 2, v60
	s_mov_b32 s4, 0
	v_add3_u32 v114, 0, v70, v65
	v_mov_b32_e32 v99, v77
	v_mov_b32_e32 v101, v77
	v_mov_b32_e32 v103, v77
	s_waitcnt vmcnt(5)
	v_mov_b32_e32 v104, v85
	v_add3_u32 v117, v65, v70, s5
	v_lshl_or_b32 v118, v57, 5, v58
	v_add_u32_e32 v119, v66, v67
	s_movk_i32 s5, 0x800
	s_movk_i32 s28, 0x2e00
	s_mov_b32 s29, 0x800000
	v_mov_b32_e32 v120, 0x3a27c5ac
	v_add_u32_e32 v121, v94, v63
	v_add_u32_e32 v122, v61, v71
	v_add_u32_e32 v123, v62, v56
	v_mov_b32_e32 v127, v77
	v_mov_b32_e32 v126, v77
	v_mov_b32_e32 v125, v77
	v_mov_b32_e32 v124, v77
	s_nop 0
	s_nop 0
	s_nop 0
	s_nop 0
	s_mov_b32 s100, 0
	s_and_saveexec_b64 s[18:19], s[10:11]
	s_cbranch_execz .LBB0_1230

.LBB0_1233:
	v_mfma_f32_16x16x32_bf16 v[56:59], v[0:3], v[32:35], 0
	v_mfma_f32_16x16x32_bf16 v[56:59], v[4:7], v[36:39], v[56:59]
	v_mfma_f32_16x16x32_bf16 v[60:63], v[8:11], v[40:43], 0
	v_mfma_f32_16x16x32_bf16 v[60:63], v[12:15], v[44:47], v[60:63]
	s_nop 5
	v_add_f32_e32 v57, v17, v57
	v_mul_f32_e32 v57, 0xbfb8aa3b, v57
	v_add_f32_e32 v56, v16, v56
	v_exp_f32_e32 v57, v57
	v_mul_f32_e32 v56, 0xbfb8aa3b, v56
	v_exp_f32_e32 v56, v56
	v_add_f32_e32 v60, v20, v60
	v_add_f32_e32 v57, 1.0, v57
	v_add_f32_e32 v58, v18, v58
	v_mul_f32_e32 v60, 0xbfb8aa3b, v60
	v_rcp_f32_e32 v57, v57
	v_mul_f32_e32 v58, 0xbfb8aa3b, v58
	v_add_f32_e32 v61, v21, v61
	v_exp_f32_e32 v60, v60
	v_add_f32_e32 v56, 1.0, v56
	v_exp_f32_e32 v58, v58
	v_mul_f32_e32 v61, 0xbfb8aa3b, v61
	v_rcp_f32_e32 v64, v56
	v_exp_f32_e32 v61, v61
	v_mul_f32_e32 v57, 0xbf1b4598, v57
	v_add_f32_e32 v59, v19, v59
	v_add_f32_e32 v60, 1.0, v60
	v_mul_f32_e32 v57, 0x3fb8aa3b, v57
	v_add_f32_e32 v58, 1.0, v58
	v_mul_f32_e32 v59, 0xbfb8aa3b, v59
	v_rcp_f32_e32 v56, v60
	v_mul_f32_e32 v60, 0xbf1b4598, v64
	v_rcp_f32_e32 v58, v58
	v_exp_f32_e32 v64, v57
	v_add_f32_e32 v57, 1.0, v61
	v_exp_f32_e32 v59, v59
	v_add_f32_e32 v61, v22, v62
	v_mul_f32_e32 v61, 0xbfb8aa3b, v61
	v_exp_f32_e32 v61, v61
	v_mul_f32_e32 v58, 0xbf1b4598, v58
	v_add_f32_e32 v59, 1.0, v59
	v_rcp_f32_e32 v59, v59
	v_mul_f32_e32 v58, 0x3fb8aa3b, v58
	v_exp_f32_e32 v62, v58
	v_add_f32_e32 v58, 1.0, v61
	v_add_f32_e32 v61, v23, v63
	v_mul_f32_e32 v61, 0xbfb8aa3b, v61
	v_exp_f32_e32 v61, v61
	v_mul_f32_e32 v59, 0xbf1b4598, v59
	v_mul_f32_e32 v60, 0x3fb8aa3b, v60
	v_mul_f32_e32 v59, 0x3fb8aa3b, v59
	v_exp_f32_e32 v60, v60
	v_exp_f32_e32 v63, v59
	v_add_f32_e32 v59, 1.0, v61
	v_rcp_f32_e32 v57, v57
	v_rcp_f32_e32 v58, v58
	v_rcp_f32_e32 v59, v59
	v_cvt_pk_f16_f32 v61, v62, v63
	v_cvt_pk_f16_f32 v60, v60, v64
	s_cmp_lg_u32 s100, 0
	s_cselect_b32 s97, 0x800, 0
	v_add_u32_e32 v168, s97, v109
	ds_write_b64 v168, v[60:61] offset:28928
	ds_write_b128 v122, v[56:59] offset:33024

.LBB0_1236:
	s_nop 0
	s_cmp_eq_u32 s4, 0
	s_cbranch_scc1 .Lrw_skipd
	s_add_i32 s98, s4, -1
	s_xor_b32 s101, s100, 0xe100
	s_cmp_lg_u32 s100, 0
	s_cselect_b32 s97, 0, 64
	v_add_u32_e32 v166, s97, v123
	s_waitcnt lgkmcnt(1)
	ds_read_b128 v[56:59], v94 offset:57856
	ds_read_b128 v[60:63], v94 offset:57872
	ds_read_b128 v[64:67], v94 offset:57888
	ds_read_b128 v[68:71], v94 offset:57904
	s_waitcnt lgkmcnt(3)
	v_add_f32_e32 v56, v56, v57
	v_add_f32_e32 v57, v58, v59
	v_add_f32_e32 v56, v56, v57
	s_waitcnt lgkmcnt(2)
	v_add_f32_e32 v57, v60, v61
	v_add_f32_e32 v58, v62, v63
	v_add_f32_e32 v57, v57, v58
	v_add_f32_e32 v56, v56, v57
	s_waitcnt lgkmcnt(1)
	v_add_f32_e32 v57, v64, v65
	v_add_f32_e32 v58, v66, v67
	v_add_f32_e32 v57, v57, v58
	s_waitcnt lgkmcnt(0)
	v_add_f32_e32 v58, v68, v69
	v_add_f32_e32 v59, v70, v71
	v_add_f32_e32 v58, v58, v59
	v_add_f32_e32 v57, v57, v58
	v_add_f32_e32 v58, v56, v57
	s_nop 1
	v_add_f32_dpp v58, v58, v58 quad_perm:[1,0,3,2] row_mask:0xf bank_mask:0xf bound_ctrl:1
	s_nop 1
	v_add_f32_dpp v58, v58, v58 quad_perm:[2,3,0,1] row_mask:0xf bank_mask:0xf bound_ctrl:1
	s_nop 1
	v_add_f32_dpp v58, v58, v58 row_half_mirror row_mask:0xf bank_mask:0xf bound_ctrl:1
	s_nop 1
	v_add_f32_dpp v58, v58, v58 row_mirror row_mask:0xf bank_mask:0xf bound_ctrl:1
	s_nop 0
	v_readlane_b32 s19, v58, 16
	v_readlane_b32 s23, v58, 48
	v_readlane_b32 s18, v58, 0
	v_readlane_b32 s22, v58, 32
	v_mov_b32_e32 v58, s19
	v_mov_b32_e32 v59, s23
	v_add_f32_e32 v58, s18, v58
	v_add_f32_e32 v59, s22, v59
	v_cndmask_b32_e64 v58, v59, v58, s[12:13]
	v_fmac_f32_e32 v57, 0xbc800000, v58
	v_fmac_f32_e32 v56, 0xbc800000, v58
	v_mul_f32_e32 v58, v57, v57
	v_fmac_f32_e32 v58, v56, v56
	s_nop 1
	v_add_f32_dpp v58, v58, v58 quad_perm:[1,0,3,2] row_mask:0xf bank_mask:0xf bound_ctrl:1
	s_nop 1
	v_add_f32_dpp v58, v58, v58 quad_perm:[2,3,0,1] row_mask:0xf bank_mask:0xf bound_ctrl:1
	s_nop 1
	v_add_f32_dpp v58, v58, v58 row_half_mirror row_mask:0xf bank_mask:0xf bound_ctrl:1
	s_nop 1
	v_add_f32_dpp v58, v58, v58 row_mirror row_mask:0xf bank_mask:0xf bound_ctrl:1
	s_nop 0
	v_readlane_b32 s22, v58, 0
	v_readlane_b32 s24, v58, 16
	v_readlane_b32 s23, v58, 32
	v_readlane_b32 s25, v58, 48
	s_and_saveexec_b64 s[18:19], s[16:17]
	s_cbranch_execz .Lrw_dend
	v_mov_b32_e32 v58, s24
	v_mov_b32_e32 v59, s25
	v_add_f32_e32 v58, s22, v58
	v_add_f32_e32 v59, s23, v59
	v_cndmask_b32_e64 v58, v59, v58, s[12:13]
	v_fmamk_f32 v58, v58, 0x3c800000, v120
	v_mul_f32_e32 v59, 0x4b800000, v58
	v_cmp_gt_f32_e32 vcc, s29, v58
	s_nop 1
	v_cndmask_b32_e32 v58, v58, v59, vcc
	v_rsq_f32_e32 v60, v58
	v_add_u32_e32 v165, s101, v121
	v_mov_b32_e32 v58, v162
	v_mov_b32_e32 v59, v163
	ds_read_b32 v105, v166 offset:57600
	ds_read_b64 v[62:63], v165 offset:37120
	v_mul_f32_e32 v61, 0x45800000, v60
	v_cndmask_b32_e32 v64, v60, v61, vcc
	v_mul_f32_e32 v60, v57, v64
	s_waitcnt lgkmcnt(2)
	v_mov_b32_e32 v61, v59
	s_waitcnt lgkmcnt(1)
	v_pk_mul_f32 v[60:61], v[104:105], v[60:61]
	v_mul_f32_e32 v56, v56, v64
	v_add_f32_e32 v57, v87, v60
	v_add_f32_e32 v57, v57, v61
	s_waitcnt lgkmcnt(0)
	v_mul_f32_e32 v59, v63, v57
	v_mov_b32_e32 v85, v105
	v_mov_b32_e32 v57, v58
	v_pk_mul_f32 v[56:57], v[84:85], v[56:57]
	s_nop 0
	v_add_f32_e32 v56, v86, v56
	v_add_f32_e32 v56, v56, v57
	v_mul_f32_e32 v56, v62, v56
	v_cvt_pk_bf16_f32 v58, v56, v59
	v_lshl_add_u32 v56, s98, 4, v95
	v_ashrrev_i32_e32 v57, 31, v56
	v_lshlrev_b64 v[56:57], 12, v[56:57]
	v_lshl_add_u64 v[56:57], v[106:107], 0, v[56:57]
	global_store_dword v[56:57], v58, off offset:2048

.Lrw_skipd:
	s_nop 0
	ds_read2_b64 v[56:59], v110 offset0:32 offset1:64
	s_waitcnt lgkmcnt(0)
	v_mov_b32_e32 v162, v58
	v_mov_b32_e32 v163, v59
	v_pk_mul_f32 v[60:61], v[78:79], v[56:57]
	s_nop 0
	v_pk_mul_f32 v[62:63], v[60:61], v[60:61]
	v_cvt_pkrtz_f16_f32 v58, v58, v58
	v_add_f32_e32 v62, v62, v63
	v_cvt_pkrtz_f16_f32 v59, v59, v59
	ds_write_b64 v112, v[58:59]
	v_add_f32_dpp v62, v62, v62 quad_perm:[1,0,3,2] row_mask:0xf bank_mask:0xf bound_ctrl:1
	s_nop 1
	v_add_f32_dpp v62, v62, v62 quad_perm:[2,3,0,1] row_mask:0xf bank_mask:0xf bound_ctrl:1
	s_nop 1
	v_add_f32_dpp v62, v62, v62 row_half_mirror row_mask:0xf bank_mask:0xf bound_ctrl:1
	s_nop 1
	v_add_f32_dpp v62, v62, v62 row_mirror row_mask:0xf bank_mask:0xf bound_ctrl:1
	s_nop 0
	v_readlane_b32 s19, v62, 16
	v_readlane_b32 s23, v62, 48
	v_readlane_b32 s18, v62, 0
	v_readlane_b32 s22, v62, 32
	v_mov_b32_e32 v62, s19
	v_mov_b32_e32 v63, s23
	v_add_f32_e32 v62, s18, v62
	v_add_f32_e32 v63, s22, v63
	v_cndmask_b32_e64 v62, v63, v62, s[12:13]
	v_mul_f32_e32 v63, 0x4b800000, v62
	v_cmp_gt_f32_e32 vcc, s29, v62
	s_nop 1
	v_cndmask_b32_e32 v62, v62, v63, vcc
	v_rsq_f32_e32 v64, v62
	ds_read_b64 v[58:59], v111
	ds_read_b64 v[62:63], v92 offset:33024
	v_mul_f32_e32 v65, 0x45800000, v64
	v_cndmask_b32_e32 v64, v64, v65, vcc
	v_min_f32_e32 v64, 0x5368d4a5, v64
	v_pk_mul_f32 v[60:61], v[60:61], v[64:65] op_sel_hi:[1,0]
	s_nop 0
	v_cvt_pk_f16_f32 v64, v60, v61
	s_waitcnt lgkmcnt(0)
	v_pk_mul_f32 v[60:61], v[62:63], v[60:61]
	s_nop 0
	v_cvt_pk_f16_f32 v60, v60, v61
	ds_write2st64_b32 v113, v64, v60 offset0:161 offset1:177
	v_pk_add_f32 v[60:61], v[62:63], -1.0 op_sel_hi:[1,0]
	s_nop 0
	v_pk_fma_f32 v[60:61], v[80:81], v[60:61], 1.0 op_sel_hi:[1,1,0]
	s_nop 0
	v_pk_mul_f32 v[56:57], v[56:57], v[60:61]
	v_cvt_pk_f16_f32 v61, v58, v59
	v_cvt_pk_f16_f32 v60, v56, v57
	v_mul_f32_e32 v57, v59, v57
	v_mul_f32_e32 v56, v58, v56
	v_mul_f32_e32 v57, v83, v57
	v_fmac_f32_e32 v57, v82, v56
	ds_write2st64_b32 v113, v60, v61 offset0:193 offset1:209
	s_nop 0
	v_add_f32_dpp v56, v57, v57 quad_perm:[1,0,3,2] row_mask:0xf bank_mask:0xf bound_ctrl:1
	s_nop 1
	v_add_f32_dpp v56, v56, v56 quad_perm:[2,3,0,1] row_mask:0xf bank_mask:0xf bound_ctrl:1
	s_nop 1
	v_add_f32_dpp v56, v56, v56 row_half_mirror row_mask:0xf bank_mask:0xf bound_ctrl:1
	s_nop 1
	v_add_f32_dpp v56, v56, v56 row_mirror row_mask:0xf bank_mask:0xf bound_ctrl:1
	s_nop 0
	v_readlane_b32 s22, v56, 0
	v_readlane_b32 s24, v56, 16
	v_readlane_b32 s23, v56, 32
	v_readlane_b32 s25, v56, 48
	s_and_saveexec_b64 s[18:19], s[14:15]
	s_cbranch_execz .LBB0_1238
	v_mov_b32_e32 v56, s24
	v_mov_b32_e32 v57, s25
	v_add_f32_e32 v56, s22, v56
	v_add_f32_e32 v57, s23, v57
	v_cndmask_b32_e64 v56, v57, v56, s[12:13]
	s_cmp_lg_u32 s100, 0
	s_cselect_b32 s97, 64, 0
	v_add_u32_e32 v166, s97, v123
	ds_write_b32 v166, v56 offset:57600
.LBB0_1238:
	s_or_b64 exec, exec, s[18:19]
	s_waitcnt lgkmcnt(0)
	s_barrier
	s_cmp_lg_u32 s100, 0
	s_cselect_b32 s97, 0x800, 0
	v_add_u32_e32 v167, s97, v114
	ds_read_b128 v[72:75], v114 offset:41216
	ds_read_b128 v[68:71], v114 offset:45312
	ds_read_b128 v[64:67], v114 offset:49408
	ds_read_b128 v[56:59], v114 offset:53504
	ds_read_b128 v[60:63], v167 offset:28928
	ds_read_b32 v85, v115
	s_waitcnt lgkmcnt(0)
	v_dot2_f32_f16 v151, v127, v72, 0
	v_dot2_f32_f16 v151, v126, v73, v151
	v_dot2_f32_f16 v151, v125, v74, v151
	v_dot2_f32_f16 v151, v124, v75, v151
	ds_read_b128 v[134:137], v114 offset:41344
	ds_read_b128 v[138:141], v114 offset:45440
	ds_read_b128 v[142:145], v114 offset:49536
	v_add_f32_dpp v151, v151, v151 quad_perm:[1,0,3,2] row_mask:0xf bank_mask:0xf bound_ctrl:1
	ds_read_b128 v[130:133], v167 offset:29056
	ds_read_b128 v[146:149], v114 offset:53632
	v_add_f32_dpp v151, v151, v151 quad_perm:[2,3,0,1] row_mask:0xf bank_mask:0xf bound_ctrl:1
	ds_read_b32 v160, v115 offset:256
	s_nop 0
	v_add_f32_dpp v151, v151, v151 row_half_mirror row_mask:0xf bank_mask:0xf bound_ctrl:1
	v_cvt_pkrtz_f16_f32 v152, -v151, -v151
	v_pk_mul_f16 v153, v152, v68
	v_pk_mul_f16 v154, v152, v69
	v_pk_mul_f16 v155, v152, v70
	v_pk_mul_f16 v156, v152, v71
	v_pk_fma_f16 v153, v85, v64, v153
	v_pk_fma_f16 v154, v85, v65, v154
	v_pk_fma_f16 v155, v85, v66, v155
	v_pk_fma_f16 v156, v85, v67, v156
	v_pk_fma_f16 v127, v127, v60, v153
	v_pk_fma_f16 v126, v126, v61, v154
	v_pk_fma_f16 v125, v125, v62, v155
	v_pk_fma_f16 v124, v124, v63, v156
	v_dot2_f32_f16 v157, v127, v56, 0
	v_dot2_f32_f16 v157, v126, v57, v157
	v_dot2_f32_f16 v157, v125, v58, v157
	v_dot2_f32_f16 v157, v124, v59, v157
	s_waitcnt lgkmcnt(0)
	v_dot2_f32_f16 v151, v127, v134, 0
	v_dot2_f32_f16 v151, v126, v135, v151
	v_dot2_f32_f16 v151, v125, v136, v151
	v_dot2_f32_f16 v151, v124, v137, v151
	ds_read_b128 v[72:75], v114 offset:41472
	ds_read_b128 v[68:71], v114 offset:45568
	ds_read_b128 v[64:67], v114 offset:49664
	v_add_f32_dpp v151, v151, v151 quad_perm:[1,0,3,2] row_mask:0xf bank_mask:0xf bound_ctrl:1
	ds_read_b128 v[60:63], v167 offset:29184
	ds_read_b128 v[56:59], v114 offset:53760
	v_add_f32_dpp v151, v151, v151 quad_perm:[2,3,0,1] row_mask:0xf bank_mask:0xf bound_ctrl:1
	ds_read_b32 v85, v115 offset:512
	ds_write_b32 v116, v157 offset:0
	v_add_f32_dpp v151, v151, v151 row_half_mirror row_mask:0xf bank_mask:0xf bound_ctrl:1
	v_cvt_pkrtz_f16_f32 v152, -v151, -v151
	v_pk_mul_f16 v153, v152, v138
	v_pk_mul_f16 v154, v152, v139
	v_pk_mul_f16 v155, v152, v140
	v_pk_mul_f16 v156, v152, v141
	v_pk_fma_f16 v153, v160, v142, v153
	v_pk_fma_f16 v154, v160, v143, v154
	v_pk_fma_f16 v155, v160, v144, v155
	v_pk_fma_f16 v156, v160, v145, v156
	v_pk_fma_f16 v127, v127, v130, v153
	v_pk_fma_f16 v126, v126, v131, v154
	v_pk_fma_f16 v125, v125, v132, v155
	v_pk_fma_f16 v124, v124, v133, v156
	v_dot2_f32_f16 v158, v127, v146, 0
	v_dot2_f32_f16 v158, v126, v147, v158
	v_dot2_f32_f16 v158, v125, v148, v158
	v_dot2_f32_f16 v158, v124, v149, v158
	s_waitcnt lgkmcnt(0)
	v_dot2_f32_f16 v151, v127, v72, 0
	v_dot2_f32_f16 v151, v126, v73, v151
	v_dot2_f32_f16 v151, v125, v74, v151
	v_dot2_f32_f16 v151, v124, v75, v151
	ds_read_b128 v[134:137], v114 offset:41600
	ds_read_b128 v[138:141], v114 offset:45696
	ds_read_b128 v[142:145], v114 offset:49792
	v_add_f32_dpp v151, v151, v151 quad_perm:[1,0,3,2] row_mask:0xf bank_mask:0xf bound_ctrl:1
	ds_read_b128 v[130:133], v167 offset:29312
	ds_read_b128 v[146:149], v114 offset:53888
	v_add_f32_dpp v151, v151, v151 quad_perm:[2,3,0,1] row_mask:0xf bank_mask:0xf bound_ctrl:1
	ds_read_b32 v160, v115 offset:768
	ds_write_b32 v116, v158 offset:2048
	v_add_f32_dpp v151, v151, v151 row_half_mirror row_mask:0xf bank_mask:0xf bound_ctrl:1
	v_cvt_pkrtz_f16_f32 v152, -v151, -v151
	v_pk_mul_f16 v153, v152, v68
	v_pk_mul_f16 v154, v152, v69
	v_pk_mul_f16 v155, v152, v70
	v_pk_mul_f16 v156, v152, v71
	v_pk_fma_f16 v153, v85, v64, v153
	v_pk_fma_f16 v154, v85, v65, v154
	v_pk_fma_f16 v155, v85, v66, v155
	v_pk_fma_f16 v156, v85, v67, v156
	v_pk_fma_f16 v127, v127, v60, v153
	v_pk_fma_f16 v126, v126, v61, v154
	v_pk_fma_f16 v125, v125, v62, v155
	v_pk_fma_f16 v124, v124, v63, v156
	v_dot2_f32_f16 v157, v127, v56, 0
	v_dot2_f32_f16 v157, v126, v57, v157
	v_dot2_f32_f16 v157, v125, v58, v157
	v_dot2_f32_f16 v157, v124, v59, v157
	s_waitcnt lgkmcnt(0)
	v_dot2_f32_f16 v151, v127, v134, 0
	v_dot2_f32_f16 v151, v126, v135, v151
	v_dot2_f32_f16 v151, v125, v136, v151
	v_dot2_f32_f16 v151, v124, v137, v151
	ds_read_b128 v[72:75], v114 offset:41728
	ds_read_b128 v[68:71], v114 offset:45824
	ds_read_b128 v[64:67], v114 offset:49920
	v_add_f32_dpp v151, v151, v151 quad_perm:[1,0,3,2] row_mask:0xf bank_mask:0xf bound_ctrl:1
	ds_read_b128 v[60:63], v167 offset:29440
	ds_read_b128 v[56:59], v114 offset:54016
	v_add_f32_dpp v151, v151, v151 quad_perm:[2,3,0,1] row_mask:0xf bank_mask:0xf bound_ctrl:1
	ds_read_b32 v85, v115 offset:1024
	ds_write_b32 v116, v157 offset:4096
	v_add_f32_dpp v151, v151, v151 row_half_mirror row_mask:0xf bank_mask:0xf bound_ctrl:1
	v_cvt_pkrtz_f16_f32 v152, -v151, -v151
	v_pk_mul_f16 v153, v152, v138
	v_pk_mul_f16 v154, v152, v139
	v_pk_mul_f16 v155, v152, v140
	v_pk_mul_f16 v156, v152, v141
	v_pk_fma_f16 v153, v160, v142, v153
	v_pk_fma_f16 v154, v160, v143, v154
	v_pk_fma_f16 v155, v160, v144, v155
	v_pk_fma_f16 v156, v160, v145, v156
	v_pk_fma_f16 v127, v127, v130, v153
	v_pk_fma_f16 v126, v126, v131, v154
	v_pk_fma_f16 v125, v125, v132, v155
	v_pk_fma_f16 v124, v124, v133, v156
	v_dot2_f32_f16 v158, v127, v146, 0
	v_dot2_f32_f16 v158, v126, v147, v158
	v_dot2_f32_f16 v158, v125, v148, v158
	v_dot2_f32_f16 v158, v124, v149, v158
	s_waitcnt lgkmcnt(0)
	v_dot2_f32_f16 v151, v127, v72, 0
	v_dot2_f32_f16 v151, v126, v73, v151
	v_dot2_f32_f16 v151, v125, v74, v151
	v_dot2_f32_f16 v151, v124, v75, v151
	ds_read_b128 v[134:137], v114 offset:41856
	ds_read_b128 v[138:141], v114 offset:45952
	ds_read_b128 v[142:145], v114 offset:50048
	v_add_f32_dpp v151, v151, v151 quad_perm:[1,0,3,2] row_mask:0xf bank_mask:0xf bound_ctrl:1
	ds_read_b128 v[130:133], v167 offset:29568
	ds_read_b128 v[146:149], v114 offset:54144
	v_add_f32_dpp v151, v151, v151 quad_perm:[2,3,0,1] row_mask:0xf bank_mask:0xf bound_ctrl:1
	ds_read_b32 v160, v115 offset:1280
	ds_write_b32 v116, v158 offset:6144
	v_add_f32_dpp v151, v151, v151 row_half_mirror row_mask:0xf bank_mask:0xf bound_ctrl:1
	v_cvt_pkrtz_f16_f32 v152, -v151, -v151
	v_pk_mul_f16 v153, v152, v68
	v_pk_mul_f16 v154, v152, v69
	v_pk_mul_f16 v155, v152, v70
	v_pk_mul_f16 v156, v152, v71
	v_pk_fma_f16 v153, v85, v64, v153
	v_pk_fma_f16 v154, v85, v65, v154
	v_pk_fma_f16 v155, v85, v66, v155
	v_pk_fma_f16 v156, v85, v67, v156
	v_pk_fma_f16 v127, v127, v60, v153
	v_pk_fma_f16 v126, v126, v61, v154
	v_pk_fma_f16 v125, v125, v62, v155
	v_pk_fma_f16 v124, v124, v63, v156
	v_dot2_f32_f16 v157, v127, v56, 0
	v_dot2_f32_f16 v157, v126, v57, v157
	v_dot2_f32_f16 v157, v125, v58, v157
	v_dot2_f32_f16 v157, v124, v59, v157
	s_waitcnt lgkmcnt(0)
	v_dot2_f32_f16 v151, v127, v134, 0
	v_dot2_f32_f16 v151, v126, v135, v151
	v_dot2_f32_f16 v151, v125, v136, v151
	v_dot2_f32_f16 v151, v124, v137, v151
	ds_read_b128 v[72:75], v114 offset:41984
	ds_read_b128 v[68:71], v114 offset:46080
	ds_read_b128 v[64:67], v114 offset:50176
	v_add_f32_dpp v151, v151, v151 quad_perm:[1,0,3,2] row_mask:0xf bank_mask:0xf bound_ctrl:1
	ds_read_b128 v[60:63], v167 offset:29696
	ds_read_b128 v[56:59], v114 offset:54272
	v_add_f32_dpp v151, v151, v151 quad_perm:[2,3,0,1] row_mask:0xf bank_mask:0xf bound_ctrl:1
	ds_read_b32 v85, v115 offset:1536
	ds_write_b32 v116, v157 offset:8192
	v_add_f32_dpp v151, v151, v151 row_half_mirror row_mask:0xf bank_mask:0xf bound_ctrl:1
	v_cvt_pkrtz_f16_f32 v152, -v151, -v151
	v_pk_mul_f16 v153, v152, v138
	v_pk_mul_f16 v154, v152, v139
	v_pk_mul_f16 v155, v152, v140
	v_pk_mul_f16 v156, v152, v141
	v_pk_fma_f16 v153, v160, v142, v153
	v_pk_fma_f16 v154, v160, v143, v154
	v_pk_fma_f16 v155, v160, v144, v155
	v_pk_fma_f16 v156, v160, v145, v156
	v_pk_fma_f16 v127, v127, v130, v153
	v_pk_fma_f16 v126, v126, v131, v154
	v_pk_fma_f16 v125, v125, v132, v155
	v_pk_fma_f16 v124, v124, v133, v156
	v_dot2_f32_f16 v158, v127, v146, 0
	v_dot2_f32_f16 v158, v126, v147, v158
	v_dot2_f32_f16 v158, v125, v148, v158
	v_dot2_f32_f16 v158, v124, v149, v158
	s_waitcnt lgkmcnt(0)
	v_dot2_f32_f16 v151, v127, v72, 0
	v_dot2_f32_f16 v151, v126, v73, v151
	v_dot2_f32_f16 v151, v125, v74, v151
	v_dot2_f32_f16 v151, v124, v75, v151
	ds_read_b128 v[134:137], v114 offset:42112
	ds_read_b128 v[138:141], v114 offset:46208
	ds_read_b128 v[142:145], v114 offset:50304
	v_add_f32_dpp v151, v151, v151 quad_perm:[1,0,3,2] row_mask:0xf bank_mask:0xf bound_ctrl:1
	ds_read_b128 v[130:133], v167 offset:29824
	ds_read_b128 v[146:149], v114 offset:54400
	v_add_f32_dpp v151, v151, v151 quad_perm:[2,3,0,1] row_mask:0xf bank_mask:0xf bound_ctrl:1
	ds_read_b32 v160, v115 offset:1792
	ds_write_b32 v116, v158 offset:10240
	v_add_f32_dpp v151, v151, v151 row_half_mirror row_mask:0xf bank_mask:0xf bound_ctrl:1
	v_cvt_pkrtz_f16_f32 v152, -v151, -v151
	v_pk_mul_f16 v153, v152, v68
	v_pk_mul_f16 v154, v152, v69
	v_pk_mul_f16 v155, v152, v70
	v_pk_mul_f16 v156, v152, v71
	v_pk_fma_f16 v153, v85, v64, v153
	v_pk_fma_f16 v154, v85, v65, v154
	v_pk_fma_f16 v155, v85, v66, v155
	v_pk_fma_f16 v156, v85, v67, v156
	v_pk_fma_f16 v127, v127, v60, v153
	v_pk_fma_f16 v126, v126, v61, v154
	v_pk_fma_f16 v125, v125, v62, v155
	v_pk_fma_f16 v124, v124, v63, v156
	v_dot2_f32_f16 v157, v127, v56, 0
	v_dot2_f32_f16 v157, v126, v57, v157
	v_dot2_f32_f16 v157, v125, v58, v157
	v_dot2_f32_f16 v157, v124, v59, v157
	s_waitcnt lgkmcnt(0)
	v_dot2_f32_f16 v151, v127, v134, 0
	v_dot2_f32_f16 v151, v126, v135, v151
	v_dot2_f32_f16 v151, v125, v136, v151
	v_dot2_f32_f16 v151, v124, v137, v151
	ds_read_b128 v[72:75], v114 offset:42240
	ds_read_b128 v[68:71], v114 offset:46336
	ds_read_b128 v[64:67], v114 offset:50432
	v_add_f32_dpp v151, v151, v151 quad_perm:[1,0,3,2] row_mask:0xf bank_mask:0xf bound_ctrl:1
	ds_read_b128 v[60:63], v167 offset:29952
	ds_read_b128 v[56:59], v114 offset:54528
	v_add_f32_dpp v151, v151, v151 quad_perm:[2,3,0,1] row_mask:0xf bank_mask:0xf bound_ctrl:1
	ds_read_b32 v85, v115 offset:2048
	ds_write_b32 v116, v157 offset:12288
	v_add_f32_dpp v151, v151, v151 row_half_mirror row_mask:0xf bank_mask:0xf bound_ctrl:1
	v_cvt_pkrtz_f16_f32 v152, -v151, -v151
	v_pk_mul_f16 v153, v152, v138
	v_pk_mul_f16 v154, v152, v139
	v_pk_mul_f16 v155, v152, v140
	v_pk_mul_f16 v156, v152, v141
	v_pk_fma_f16 v153, v160, v142, v153
	v_pk_fma_f16 v154, v160, v143, v154
	v_pk_fma_f16 v155, v160, v144, v155
	v_pk_fma_f16 v156, v160, v145, v156
	v_pk_fma_f16 v127, v127, v130, v153
	v_pk_fma_f16 v126, v126, v131, v154
	v_pk_fma_f16 v125, v125, v132, v155
	v_pk_fma_f16 v124, v124, v133, v156
	v_dot2_f32_f16 v158, v127, v146, 0
	v_dot2_f32_f16 v158, v126, v147, v158
	v_dot2_f32_f16 v158, v125, v148, v158
	v_dot2_f32_f16 v158, v124, v149, v158
	s_waitcnt lgkmcnt(0)
	v_dot2_f32_f16 v151, v127, v72, 0
	v_dot2_f32_f16 v151, v126, v73, v151
	v_dot2_f32_f16 v151, v125, v74, v151
	v_dot2_f32_f16 v151, v124, v75, v151
	ds_read_b128 v[134:137], v114 offset:42368
	ds_read_b128 v[138:141], v114 offset:46464
	ds_read_b128 v[142:145], v114 offset:50560
	v_add_f32_dpp v151, v151, v151 quad_perm:[1,0,3,2] row_mask:0xf bank_mask:0xf bound_ctrl:1
	ds_read_b128 v[130:133], v167 offset:30080
	ds_read_b128 v[146:149], v114 offset:54656
	v_add_f32_dpp v151, v151, v151 quad_perm:[2,3,0,1] row_mask:0xf bank_mask:0xf bound_ctrl:1
	ds_read_b32 v160, v115 offset:2304
	ds_write_b32 v116, v158 offset:14336
	v_add_f32_dpp v151, v151, v151 row_half_mirror row_mask:0xf bank_mask:0xf bound_ctrl:1
	v_cvt_pkrtz_f16_f32 v152, -v151, -v151
	v_pk_mul_f16 v153, v152, v68
	v_pk_mul_f16 v154, v152, v69
	v_pk_mul_f16 v155, v152, v70
	v_pk_mul_f16 v156, v152, v71
	v_pk_fma_f16 v153, v85, v64, v153
	v_pk_fma_f16 v154, v85, v65, v154
	v_pk_fma_f16 v155, v85, v66, v155
	v_pk_fma_f16 v156, v85, v67, v156
	v_pk_fma_f16 v127, v127, v60, v153
	v_pk_fma_f16 v126, v126, v61, v154
	v_pk_fma_f16 v125, v125, v62, v155
	v_pk_fma_f16 v124, v124, v63, v156
	v_dot2_f32_f16 v157, v127, v56, 0
	v_dot2_f32_f16 v157, v126, v57, v157
	v_dot2_f32_f16 v157, v125, v58, v157
	v_dot2_f32_f16 v157, v124, v59, v157
	s_waitcnt lgkmcnt(0)
	v_dot2_f32_f16 v151, v127, v134, 0
	v_dot2_f32_f16 v151, v126, v135, v151
	v_dot2_f32_f16 v151, v125, v136, v151
	v_dot2_f32_f16 v151, v124, v137, v151
	ds_read_b128 v[72:75], v114 offset:42496
	ds_read_b128 v[68:71], v114 offset:46592
	ds_read_b128 v[64:67], v114 offset:50688
	v_add_f32_dpp v151, v151, v151 quad_perm:[1,0,3,2] row_mask:0xf bank_mask:0xf bound_ctrl:1
	ds_read_b128 v[60:63], v167 offset:30208
	ds_read_b128 v[56:59], v114 offset:54784
	v_add_f32_dpp v151, v151, v151 quad_perm:[2,3,0,1] row_mask:0xf bank_mask:0xf bound_ctrl:1
	ds_read_b32 v85, v115 offset:2560
	ds_write_b32 v116, v157 offset:16384
	v_add_f32_dpp v151, v151, v151 row_half_mirror row_mask:0xf bank_mask:0xf bound_ctrl:1
	v_cvt_pkrtz_f16_f32 v152, -v151, -v151
	v_pk_mul_f16 v153, v152, v138
	v_pk_mul_f16 v154, v152, v139
	v_pk_mul_f16 v155, v152, v140
	v_pk_mul_f16 v156, v152, v141
	v_pk_fma_f16 v153, v160, v142, v153
	v_pk_fma_f16 v154, v160, v143, v154
	v_pk_fma_f16 v155, v160, v144, v155
	v_pk_fma_f16 v156, v160, v145, v156
	v_pk_fma_f16 v127, v127, v130, v153
	v_pk_fma_f16 v126, v126, v131, v154
	v_pk_fma_f16 v125, v125, v132, v155
	v_pk_fma_f16 v124, v124, v133, v156
	v_dot2_f32_f16 v158, v127, v146, 0
	v_dot2_f32_f16 v158, v126, v147, v158
	v_dot2_f32_f16 v158, v125, v148, v158
	v_dot2_f32_f16 v158, v124, v149, v158
	s_waitcnt lgkmcnt(0)
	v_dot2_f32_f16 v151, v127, v72, 0
	v_dot2_f32_f16 v151, v126, v73, v151
	v_dot2_f32_f16 v151, v125, v74, v151
	v_dot2_f32_f16 v151, v124, v75, v151
	ds_read_b128 v[134:137], v114 offset:42624
	ds_read_b128 v[138:141], v114 offset:46720
	ds_read_b128 v[142:145], v114 offset:50816
	v_add_f32_dpp v151, v151, v151 quad_perm:[1,0,3,2] row_mask:0xf bank_mask:0xf bound_ctrl:1
	ds_read_b128 v[130:133], v167 offset:30336
	ds_read_b128 v[146:149], v114 offset:54912
	v_add_f32_dpp v151, v151, v151 quad_perm:[2,3,0,1] row_mask:0xf bank_mask:0xf bound_ctrl:1
	ds_read_b32 v160, v115 offset:2816
	ds_write_b32 v116, v158 offset:18432
	v_add_f32_dpp v151, v151, v151 row_half_mirror row_mask:0xf bank_mask:0xf bound_ctrl:1
	v_cvt_pkrtz_f16_f32 v152, -v151, -v151
	v_pk_mul_f16 v153, v152, v68
	v_pk_mul_f16 v154, v152, v69
	v_pk_mul_f16 v155, v152, v70
	v_pk_mul_f16 v156, v152, v71
	v_pk_fma_f16 v153, v85, v64, v153
	v_pk_fma_f16 v154, v85, v65, v154
	v_pk_fma_f16 v155, v85, v66, v155
	v_pk_fma_f16 v156, v85, v67, v156
	v_pk_fma_f16 v127, v127, v60, v153
	v_pk_fma_f16 v126, v126, v61, v154
	v_pk_fma_f16 v125, v125, v62, v155
	v_pk_fma_f16 v124, v124, v63, v156
	v_dot2_f32_f16 v157, v127, v56, 0
	v_dot2_f32_f16 v157, v126, v57, v157
	v_dot2_f32_f16 v157, v125, v58, v157
	v_dot2_f32_f16 v157, v124, v59, v157
	s_waitcnt lgkmcnt(0)
	v_dot2_f32_f16 v151, v127, v134, 0
	v_dot2_f32_f16 v151, v126, v135, v151
	v_dot2_f32_f16 v151, v125, v136, v151
	v_dot2_f32_f16 v151, v124, v137, v151
	ds_read_b128 v[72:75], v114 offset:42752
	ds_read_b128 v[68:71], v114 offset:46848
	ds_read_b128 v[64:67], v114 offset:50944
	v_add_f32_dpp v151, v151, v151 quad_perm:[1,0,3,2] row_mask:0xf bank_mask:0xf bound_ctrl:1
	ds_read_b128 v[60:63], v167 offset:30464
	ds_read_b128 v[56:59], v114 offset:55040
	v_add_f32_dpp v151, v151, v151 quad_perm:[2,3,0,1] row_mask:0xf bank_mask:0xf bound_ctrl:1
	ds_read_b32 v85, v115 offset:3072
	ds_write_b32 v116, v157 offset:20480
	v_add_f32_dpp v151, v151, v151 row_half_mirror row_mask:0xf bank_mask:0xf bound_ctrl:1
	v_cvt_pkrtz_f16_f32 v152, -v151, -v151
	v_pk_mul_f16 v153, v152, v138
	v_pk_mul_f16 v154, v152, v139
	v_pk_mul_f16 v155, v152, v140
	v_pk_mul_f16 v156, v152, v141
	v_pk_fma_f16 v153, v160, v142, v153
	v_pk_fma_f16 v154, v160, v143, v154
	v_pk_fma_f16 v155, v160, v144, v155
	v_pk_fma_f16 v156, v160, v145, v156
	v_pk_fma_f16 v127, v127, v130, v153
	v_pk_fma_f16 v126, v126, v131, v154
	v_pk_fma_f16 v125, v125, v132, v155
	v_pk_fma_f16 v124, v124, v133, v156
	v_dot2_f32_f16 v158, v127, v146, 0
	v_dot2_f32_f16 v158, v126, v147, v158
	v_dot2_f32_f16 v158, v125, v148, v158
	v_dot2_f32_f16 v158, v124, v149, v158
	s_waitcnt lgkmcnt(0)
	v_dot2_f32_f16 v151, v127, v72, 0
	v_dot2_f32_f16 v151, v126, v73, v151
	v_dot2_f32_f16 v151, v125, v74, v151
	v_dot2_f32_f16 v151, v124, v75, v151
	ds_read_b128 v[134:137], v114 offset:42880
	ds_read_b128 v[138:141], v114 offset:46976
	ds_read_b128 v[142:145], v114 offset:51072
	v_add_f32_dpp v151, v151, v151 quad_perm:[1,0,3,2] row_mask:0xf bank_mask:0xf bound_ctrl:1
	ds_read_b128 v[130:133], v167 offset:30592
	ds_read_b128 v[146:149], v114 offset:55168
	v_add_f32_dpp v151, v151, v151 quad_perm:[2,3,0,1] row_mask:0xf bank_mask:0xf bound_ctrl:1
	ds_read_b32 v160, v115 offset:3328
	ds_write_b32 v116, v158 offset:22528
	v_add_f32_dpp v151, v151, v151 row_half_mirror row_mask:0xf bank_mask:0xf bound_ctrl:1
	v_cvt_pkrtz_f16_f32 v152, -v151, -v151
	v_pk_mul_f16 v153, v152, v68
	v_pk_mul_f16 v154, v152, v69
	v_pk_mul_f16 v155, v152, v70
	v_pk_mul_f16 v156, v152, v71
	v_pk_fma_f16 v153, v85, v64, v153
	v_pk_fma_f16 v154, v85, v65, v154
	v_pk_fma_f16 v155, v85, v66, v155
	v_pk_fma_f16 v156, v85, v67, v156
	v_pk_fma_f16 v127, v127, v60, v153
	v_pk_fma_f16 v126, v126, v61, v154
	v_pk_fma_f16 v125, v125, v62, v155
	v_pk_fma_f16 v124, v124, v63, v156
	v_dot2_f32_f16 v157, v127, v56, 0
	v_dot2_f32_f16 v157, v126, v57, v157
	v_dot2_f32_f16 v157, v125, v58, v157
	v_dot2_f32_f16 v157, v124, v59, v157
	s_waitcnt lgkmcnt(0)
	v_dot2_f32_f16 v151, v127, v134, 0
	v_dot2_f32_f16 v151, v126, v135, v151
	v_dot2_f32_f16 v151, v125, v136, v151
	v_dot2_f32_f16 v151, v124, v137, v151
	ds_read_b128 v[72:75], v114 offset:43008
	ds_read_b128 v[68:71], v114 offset:47104
	ds_read_b128 v[64:67], v114 offset:51200
	v_add_f32_dpp v151, v151, v151 quad_perm:[1,0,3,2] row_mask:0xf bank_mask:0xf bound_ctrl:1
	ds_read_b128 v[60:63], v167 offset:30720
	ds_read_b128 v[56:59], v114 offset:55296
	v_add_f32_dpp v151, v151, v151 quad_perm:[2,3,0,1] row_mask:0xf bank_mask:0xf bound_ctrl:1
	ds_read_b32 v85, v115 offset:3584
	ds_write_b32 v116, v157 offset:24576
	v_add_f32_dpp v151, v151, v151 row_half_mirror row_mask:0xf bank_mask:0xf bound_ctrl:1
	v_cvt_pkrtz_f16_f32 v152, -v151, -v151
	v_pk_mul_f16 v153, v152, v138
	v_pk_mul_f16 v154, v152, v139
	v_pk_mul_f16 v155, v152, v140
	v_pk_mul_f16 v156, v152, v141
	v_pk_fma_f16 v153, v160, v142, v153
	v_pk_fma_f16 v154, v160, v143, v154
	v_pk_fma_f16 v155, v160, v144, v155
	v_pk_fma_f16 v156, v160, v145, v156
	v_pk_fma_f16 v127, v127, v130, v153
	v_pk_fma_f16 v126, v126, v131, v154
	v_pk_fma_f16 v125, v125, v132, v155
	v_pk_fma_f16 v124, v124, v133, v156
	v_dot2_f32_f16 v158, v127, v146, 0
	v_dot2_f32_f16 v158, v126, v147, v158
	v_dot2_f32_f16 v158, v125, v148, v158
	v_dot2_f32_f16 v158, v124, v149, v158
	s_waitcnt lgkmcnt(0)
	v_dot2_f32_f16 v151, v127, v72, 0
	v_dot2_f32_f16 v151, v126, v73, v151
	v_dot2_f32_f16 v151, v125, v74, v151
	v_dot2_f32_f16 v151, v124, v75, v151
	ds_read_b128 v[134:137], v114 offset:43136
	ds_read_b128 v[138:141], v114 offset:47232
	ds_read_b128 v[142:145], v114 offset:51328
	v_add_f32_dpp v151, v151, v151 quad_perm:[1,0,3,2] row_mask:0xf bank_mask:0xf bound_ctrl:1
	ds_read_b128 v[130:133], v167 offset:30848
	ds_read_b128 v[146:149], v114 offset:55424
	v_add_f32_dpp v151, v151, v151 quad_perm:[2,3,0,1] row_mask:0xf bank_mask:0xf bound_ctrl:1
	ds_read_b32 v160, v115 offset:3840
	ds_write_b32 v116, v158 offset:26624
	v_add_f32_dpp v151, v151, v151 row_half_mirror row_mask:0xf bank_mask:0xf bound_ctrl:1
	v_cvt_pkrtz_f16_f32 v152, -v151, -v151
	v_pk_mul_f16 v153, v152, v68
	v_pk_mul_f16 v154, v152, v69
	v_pk_mul_f16 v155, v152, v70
	v_pk_mul_f16 v156, v152, v71
	v_pk_fma_f16 v153, v85, v64, v153
	v_pk_fma_f16 v154, v85, v65, v154
	v_pk_fma_f16 v155, v85, v66, v155
	v_pk_fma_f16 v156, v85, v67, v156
	v_pk_fma_f16 v127, v127, v60, v153
	v_pk_fma_f16 v126, v126, v61, v154
	v_pk_fma_f16 v125, v125, v62, v155
	v_pk_fma_f16 v124, v124, v63, v156
	v_dot2_f32_f16 v157, v127, v56, 0
	v_dot2_f32_f16 v157, v126, v57, v157
	v_dot2_f32_f16 v157, v125, v58, v157
	v_dot2_f32_f16 v157, v124, v59, v157
	s_waitcnt lgkmcnt(0)
	v_dot2_f32_f16 v151, v127, v134, 0
	v_dot2_f32_f16 v151, v126, v135, v151
	v_dot2_f32_f16 v151, v125, v136, v151
	v_dot2_f32_f16 v151, v124, v137, v151
	s_nop 2
	v_add_f32_dpp v151, v151, v151 quad_perm:[1,0,3,2] row_mask:0xf bank_mask:0xf bound_ctrl:1
	s_nop 1
	v_add_f32_dpp v151, v151, v151 quad_perm:[2,3,0,1] row_mask:0xf bank_mask:0xf bound_ctrl:1
	s_nop 0
	ds_write_b32 v116, v157 offset:28672
	v_add_f32_dpp v151, v151, v151 row_half_mirror row_mask:0xf bank_mask:0xf bound_ctrl:1
	v_cvt_pkrtz_f16_f32 v152, -v151, -v151
	v_pk_mul_f16 v153, v152, v138
	v_pk_mul_f16 v154, v152, v139
	v_pk_mul_f16 v155, v152, v140
	v_pk_mul_f16 v156, v152, v141
	v_pk_fma_f16 v153, v160, v142, v153
	v_pk_fma_f16 v154, v160, v143, v154
	v_pk_fma_f16 v155, v160, v144, v155
	v_pk_fma_f16 v156, v160, v145, v156
	v_pk_fma_f16 v127, v127, v130, v153
	v_pk_fma_f16 v126, v126, v131, v154
	v_pk_fma_f16 v125, v125, v132, v155
	v_pk_fma_f16 v124, v124, v133, v156
	v_dot2_f32_f16 v158, v127, v146, 0
	v_dot2_f32_f16 v158, v126, v147, v158
	v_dot2_f32_f16 v158, v125, v148, v158
	v_dot2_f32_f16 v158, v124, v149, v158
	s_nop 2
	ds_write_b32 v116, v158 offset:30720
	s_xor_b32 s100, s100, 0xe100
	s_cmpk_lg_i32 s30, 0x80
	s_cbranch_scc0 .LBB0_1250
	s_mov_b32 s4, s30
	s_and_saveexec_b64 s[18:19], s[10:11]
	s_cbranch_execnz .LBB0_1229
	s_branch .LBB0_1230

.LBB0_1250:
	s_waitcnt lgkmcnt(0)
	s_barrier
	s_movk_i32 s98, 0x7f
	s_xor_b32 s101, s100, 0xe100
	s_cmp_lg_u32 s100, 0
	s_cselect_b32 s97, 0, 64
	v_add_u32_e32 v166, s97, v123
	s_waitcnt lgkmcnt(1)
	ds_read_b128 v[56:59], v94 offset:57856
	ds_read_b128 v[60:63], v94 offset:57872
	ds_read_b128 v[64:67], v94 offset:57888
	ds_read_b128 v[68:71], v94 offset:57904
	s_waitcnt lgkmcnt(3)
	v_add_f32_e32 v56, v56, v57
	v_add_f32_e32 v57, v58, v59
	v_add_f32_e32 v56, v56, v57
	s_waitcnt lgkmcnt(2)
	v_add_f32_e32 v57, v60, v61
	v_add_f32_e32 v58, v62, v63
	v_add_f32_e32 v57, v57, v58
	v_add_f32_e32 v56, v56, v57
	s_waitcnt lgkmcnt(1)
	v_add_f32_e32 v57, v64, v65
	v_add_f32_e32 v58, v66, v67
	v_add_f32_e32 v57, v57, v58
	s_waitcnt lgkmcnt(0)
	v_add_f32_e32 v58, v68, v69
	v_add_f32_e32 v59, v70, v71
	v_add_f32_e32 v58, v58, v59
	v_add_f32_e32 v57, v57, v58
	v_add_f32_e32 v58, v56, v57
	s_nop 1
	v_add_f32_dpp v58, v58, v58 quad_perm:[1,0,3,2] row_mask:0xf bank_mask:0xf bound_ctrl:1
	s_nop 1
	v_add_f32_dpp v58, v58, v58 quad_perm:[2,3,0,1] row_mask:0xf bank_mask:0xf bound_ctrl:1
	s_nop 1
	v_add_f32_dpp v58, v58, v58 row_half_mirror row_mask:0xf bank_mask:0xf bound_ctrl:1
	s_nop 1
	v_add_f32_dpp v58, v58, v58 row_mirror row_mask:0xf bank_mask:0xf bound_ctrl:1
	s_nop 0
	v_readlane_b32 s19, v58, 16
	v_readlane_b32 s23, v58, 48
	v_readlane_b32 s18, v58, 0
	v_readlane_b32 s22, v58, 32
	v_mov_b32_e32 v58, s19
	v_mov_b32_e32 v59, s23
	v_add_f32_e32 v58, s18, v58
	v_add_f32_e32 v59, s22, v59
	v_cndmask_b32_e64 v58, v59, v58, s[12:13]
	v_fmac_f32_e32 v57, 0xbc800000, v58
	v_fmac_f32_e32 v56, 0xbc800000, v58
	v_mul_f32_e32 v58, v57, v57
	v_fmac_f32_e32 v58, v56, v56
	s_nop 1
	v_add_f32_dpp v58, v58, v58 quad_perm:[1,0,3,2] row_mask:0xf bank_mask:0xf bound_ctrl:1
	s_nop 1
	v_add_f32_dpp v58, v58, v58 quad_perm:[2,3,0,1] row_mask:0xf bank_mask:0xf bound_ctrl:1
	s_nop 1
	v_add_f32_dpp v58, v58, v58 row_half_mirror row_mask:0xf bank_mask:0xf bound_ctrl:1
	s_nop 1
	v_add_f32_dpp v58, v58, v58 row_mirror row_mask:0xf bank_mask:0xf bound_ctrl:1
	s_nop 0
	v_readlane_b32 s22, v58, 0
	v_readlane_b32 s24, v58, 16
	v_readlane_b32 s23, v58, 32
	v_readlane_b32 s25, v58, 48
	s_and_saveexec_b64 s[18:19], s[16:17]
	s_cbranch_execz .Lrw_dend2
	v_mov_b32_e32 v58, s24
	v_mov_b32_e32 v59, s25
	v_add_f32_e32 v58, s22, v58
	v_add_f32_e32 v59, s23, v59
	v_cndmask_b32_e64 v58, v59, v58, s[12:13]
	v_fmamk_f32 v58, v58, 0x3c800000, v120
	v_mul_f32_e32 v59, 0x4b800000, v58
	v_cmp_gt_f32_e32 vcc, s29, v58
	s_nop 1
	v_cndmask_b32_e32 v58, v58, v59, vcc
	v_rsq_f32_e32 v60, v58
	v_add_u32_e32 v165, s101, v121
	v_mov_b32_e32 v58, v162
	v_mov_b32_e32 v59, v163
	ds_read_b32 v105, v166 offset:57600
	ds_read_b64 v[62:63], v165 offset:37120
	v_mul_f32_e32 v61, 0x45800000, v60
	v_cndmask_b32_e32 v64, v60, v61, vcc
	v_mul_f32_e32 v60, v57, v64
	s_waitcnt lgkmcnt(2)
	v_mov_b32_e32 v61, v59
	s_waitcnt lgkmcnt(1)
	v_pk_mul_f32 v[60:61], v[104:105], v[60:61]
	v_mul_f32_e32 v56, v56, v64
	v_add_f32_e32 v57, v87, v60
	v_add_f32_e32 v57, v57, v61
	s_waitcnt lgkmcnt(0)
	v_mul_f32_e32 v59, v63, v57
	v_mov_b32_e32 v85, v105
	v_mov_b32_e32 v57, v58
	v_pk_mul_f32 v[56:57], v[84:85], v[56:57]
	s_nop 0
	v_add_f32_e32 v56, v86, v56
	v_add_f32_e32 v56, v56, v57
	v_mul_f32_e32 v56, v62, v56
	v_cvt_pk_bf16_f32 v58, v56, v59
	v_lshl_add_u32 v56, s98, 4, v95
	v_ashrrev_i32_e32 v57, 31, v56
	v_lshlrev_b64 v[56:57], 12, v[56:57]
	v_lshl_add_u64 v[56:57], v[106:107], 0, v[56:57]
	global_store_dword v[56:57], v58, off offset:2048
.Lrw_dend2:
	s_or_b64 exec, exec, s[18:19]
	s_ashr_i32 s3, s2, 31
	s_lshl_b64 s[4:5], s[2:3], 14
	s_add_u32 s4, s20, s4
	v_lshlrev_b32_e32 v4, 6, v108
	s_addc_u32 s5, s21, s5
	v_ashrrev_i32_e32 v5, 31, v4
	v_cvt_f32_f16_sdwa v1, v127 dst_sel:DWORD dst_unused:UNUSED_PAD src0_sel:WORD_1
	v_cvt_f32_f16_e32 v0, v127
	v_cvt_f32_f16_sdwa v3, v126 dst_sel:DWORD dst_unused:UNUSED_PAD src0_sel:WORD_1
	v_cvt_f32_f16_e32 v2, v126
	v_lshl_add_u64 v[4:5], v[4:5], 2, s[4:5]
	v_lshlrev_b32_e32 v6, 5, v93
	v_mov_b32_e32 v7, 0
	v_lshl_add_u64 v[8:9], v[4:5], 0, v[6:7]
	s_mov_b64 s[4:5], 0x4824000
	s_mov_b32 s3, 0x4824000
	v_cvt_f32_f16_sdwa v5, v125 dst_sel:DWORD dst_unused:UNUSED_PAD src0_sel:WORD_1
	v_cvt_f32_f16_e32 v4, v125
	v_cvt_f32_f16_sdwa v7, v124 dst_sel:DWORD dst_unused:UNUSED_PAD src0_sel:WORD_1
	v_cvt_f32_f16_e32 v6, v124
	v_lshl_add_u64 v[10:11], v[8:9], 0, s[4:5]
	v_add_co_u32_e32 v8, vcc, s3, v8
	s_nop 1
	v_addc_co_u32_e32 v9, vcc, 0, v9, vcc
	global_store_dwordx4 v[8:9], v[0:3], off
	global_store_dwordx4 v[10:11], v[4:7], off offset:16
	s_cmpk_lt_i32 s2, 0x80
	s_cbranch_scc1 .LBB0_1403
